# mods partial GEMV: silu(c[k]) computed once lane-parallel and broadcast by v_readlane into SGPR fma operands, 56-deep w_mod row-load ring; plus the 32-loads-in-flight transposes
# speedup vs baseline: 1.0105x; 1.0051x over previous
; __device__ __forceinline__ float fsilu(float x) { return x * fsig(x); }
; __global__ void __launch_bounds__(512, 2) fwd_megakernel(Params Parg) {
;     ...
;                 r -= NCONV; const int kc = r / 144, nc = r % 144, n = nc * 64 + lane;
;                 float a0 = 0.f, a1 = 0.f, a2 = 0.f;
;                 for (int k = kc * 128; k < kc * 128 + 128; ++k) { const float w = __builtin_nontemporal_load(&w_mod[(size_t)k * (NMOD * D) + n]); a0 += fsilu(cvec[k]) * w; a1 += fsilu(cvec[D + k]) * w; a2 += fsilu(cctx[k]) * w; }
.LBB0_146:
	s_andn2_b64 vcc, exec, s[6:7]
	s_cbranch_vccnz .LBB0_7
	s_and_b32 s6, 0xffff, s4
	s_mul_hi_u32 s6, s6, 0x1c71c72
	s_lshl_b32 s30, s6, 7
	s_add_i32 s6, s3, 0xc300
	s_and_b32 s7, s6, 0xffff
	s_mul_i32 s24, s7, 0xe38f
	s_lshr_b32 s24, s24, 23
	s_mul_i32 s31, s24, 0x90
	s_sub_i32 s6, s6, s31
	s_lshl_b32 s6, s6, 6
	s_and_b32 s6, s6, 0xffc0
	s_mul_hi_u32 s35, s7, 0x1c71c72
	v_or_b32_e32 v28, s6, v1
	s_lshl_b32 s31, s24, 7
	s_mul_i32 s6, s35, 0x480000
	s_add_u32 s6, s10, s6
	v_lshlrev_b32_e32 v8, 2, v28
	s_addc_u32 s7, s11, 0
	v_lshl_add_u64 v[2:3], s[6:7], 0, v[8:9]
	s_sub_i32 s6, s30, s31
	v_mov_b32_e32 v29, 0
	s_add_i32 s34, s6, 0x80
	s_lshl_b32 s35, s35, 9
	s_mov_b64 s[6:7], s[8:9]
	s_mov_b64 s[30:31], s[20:21]
	v_mov_b32_e32 v4, 0
	v_mov_b32_e32 v5, v29
	s_add_u32 s56, s30, s35
	s_addc_u32 s57, s31, 0
	s_add_u32 s58, s6, s35
	s_addc_u32 s59, s7, 0
	s_mov_b32 s60, 0x9000
	s_mov_b32 s61, 0
	v_lshlrev_b32_e32 v210, 2, v1
	v_add_u32_e32 v213, 0x1000, v210
	global_load_dword v211, v210, s[56:57]
	global_load_dword v212, v210, s[56:57] offset:256
	global_load_dword v214, v213, s[56:57]
	global_load_dword v215, v213, s[56:57] offset:256
	global_load_dword v216, v210, s[58:59] offset:-4
	global_load_dword v217, v210, s[58:59] offset:252
	global_load_dword v80, v[2:3], off nt
	v_lshl_add_u64 v[2:3], v[2:3], 0, s[60:61]
	global_load_dword v81, v[2:3], off nt
	v_lshl_add_u64 v[2:3], v[2:3], 0, s[60:61]
	global_load_dword v82, v[2:3], off nt
	v_lshl_add_u64 v[2:3], v[2:3], 0, s[60:61]
	global_load_dword v83, v[2:3], off nt
	v_lshl_add_u64 v[2:3], v[2:3], 0, s[60:61]
	global_load_dword v84, v[2:3], off nt
	v_lshl_add_u64 v[2:3], v[2:3], 0, s[60:61]
	global_load_dword v85, v[2:3], off nt
	v_lshl_add_u64 v[2:3], v[2:3], 0, s[60:61]
	global_load_dword v86, v[2:3], off nt
	v_lshl_add_u64 v[2:3], v[2:3], 0, s[60:61]
	global_load_dword v87, v[2:3], off nt
	v_lshl_add_u64 v[2:3], v[2:3], 0, s[60:61]
	global_load_dword v88, v[2:3], off nt
	v_lshl_add_u64 v[2:3], v[2:3], 0, s[60:61]
	global_load_dword v89, v[2:3], off nt
	v_lshl_add_u64 v[2:3], v[2:3], 0, s[60:61]
	global_load_dword v90, v[2:3], off nt
	v_lshl_add_u64 v[2:3], v[2:3], 0, s[60:61]
	global_load_dword v91, v[2:3], off nt
	v_lshl_add_u64 v[2:3], v[2:3], 0, s[60:61]
	global_load_dword v92, v[2:3], off nt
	v_lshl_add_u64 v[2:3], v[2:3], 0, s[60:61]
	global_load_dword v93, v[2:3], off nt
	v_lshl_add_u64 v[2:3], v[2:3], 0, s[60:61]
	global_load_dword v94, v[2:3], off nt
	v_lshl_add_u64 v[2:3], v[2:3], 0, s[60:61]
	global_load_dword v95, v[2:3], off nt
	v_lshl_add_u64 v[2:3], v[2:3], 0, s[60:61]
	global_load_dword v96, v[2:3], off nt
	v_lshl_add_u64 v[2:3], v[2:3], 0, s[60:61]
	global_load_dword v97, v[2:3], off nt
	v_lshl_add_u64 v[2:3], v[2:3], 0, s[60:61]
	global_load_dword v98, v[2:3], off nt
	v_lshl_add_u64 v[2:3], v[2:3], 0, s[60:61]
	global_load_dword v99, v[2:3], off nt
	v_lshl_add_u64 v[2:3], v[2:3], 0, s[60:61]
	global_load_dword v100, v[2:3], off nt
	v_lshl_add_u64 v[2:3], v[2:3], 0, s[60:61]
	global_load_dword v101, v[2:3], off nt
	v_lshl_add_u64 v[2:3], v[2:3], 0, s[60:61]
	global_load_dword v102, v[2:3], off nt
	v_lshl_add_u64 v[2:3], v[2:3], 0, s[60:61]
	global_load_dword v103, v[2:3], off nt
	v_lshl_add_u64 v[2:3], v[2:3], 0, s[60:61]
	global_load_dword v104, v[2:3], off nt
	v_lshl_add_u64 v[2:3], v[2:3], 0, s[60:61]
	global_load_dword v105, v[2:3], off nt
	v_lshl_add_u64 v[2:3], v[2:3], 0, s[60:61]
	global_load_dword v106, v[2:3], off nt
	v_lshl_add_u64 v[2:3], v[2:3], 0, s[60:61]
	global_load_dword v107, v[2:3], off nt
	v_lshl_add_u64 v[2:3], v[2:3], 0, s[60:61]
	global_load_dword v108, v[2:3], off nt
	v_lshl_add_u64 v[2:3], v[2:3], 0, s[60:61]
	global_load_dword v109, v[2:3], off nt
	v_lshl_add_u64 v[2:3], v[2:3], 0, s[60:61]
	global_load_dword v110, v[2:3], off nt
	v_lshl_add_u64 v[2:3], v[2:3], 0, s[60:61]
	global_load_dword v111, v[2:3], off nt
	v_lshl_add_u64 v[2:3], v[2:3], 0, s[60:61]
	global_load_dword v112, v[2:3], off nt
	v_lshl_add_u64 v[2:3], v[2:3], 0, s[60:61]
	global_load_dword v113, v[2:3], off nt
	v_lshl_add_u64 v[2:3], v[2:3], 0, s[60:61]
	global_load_dword v114, v[2:3], off nt
	v_lshl_add_u64 v[2:3], v[2:3], 0, s[60:61]
	global_load_dword v115, v[2:3], off nt
	v_lshl_add_u64 v[2:3], v[2:3], 0, s[60:61]
	global_load_dword v116, v[2:3], off nt
	v_lshl_add_u64 v[2:3], v[2:3], 0, s[60:61]
	global_load_dword v117, v[2:3], off nt
	v_lshl_add_u64 v[2:3], v[2:3], 0, s[60:61]
	global_load_dword v118, v[2:3], off nt
	v_lshl_add_u64 v[2:3], v[2:3], 0, s[60:61]
	global_load_dword v119, v[2:3], off nt
	v_lshl_add_u64 v[2:3], v[2:3], 0, s[60:61]
	global_load_dword v120, v[2:3], off nt
	v_lshl_add_u64 v[2:3], v[2:3], 0, s[60:61]
	global_load_dword v121, v[2:3], off nt
	v_lshl_add_u64 v[2:3], v[2:3], 0, s[60:61]
	global_load_dword v122, v[2:3], off nt
	v_lshl_add_u64 v[2:3], v[2:3], 0, s[60:61]
	global_load_dword v123, v[2:3], off nt
	v_lshl_add_u64 v[2:3], v[2:3], 0, s[60:61]
	global_load_dword v124, v[2:3], off nt
	v_lshl_add_u64 v[2:3], v[2:3], 0, s[60:61]
	global_load_dword v125, v[2:3], off nt
	v_lshl_add_u64 v[2:3], v[2:3], 0, s[60:61]
	global_load_dword v126, v[2:3], off nt
	v_lshl_add_u64 v[2:3], v[2:3], 0, s[60:61]
	global_load_dword v127, v[2:3], off nt
	v_lshl_add_u64 v[2:3], v[2:3], 0, s[60:61]
	global_load_dword v128, v[2:3], off nt
	v_lshl_add_u64 v[2:3], v[2:3], 0, s[60:61]
	global_load_dword v129, v[2:3], off nt
	v_lshl_add_u64 v[2:3], v[2:3], 0, s[60:61]
	global_load_dword v130, v[2:3], off nt
	v_lshl_add_u64 v[2:3], v[2:3], 0, s[60:61]
	global_load_dword v131, v[2:3], off nt
	v_lshl_add_u64 v[2:3], v[2:3], 0, s[60:61]
	global_load_dword v132, v[2:3], off nt
	v_lshl_add_u64 v[2:3], v[2:3], 0, s[60:61]
	global_load_dword v133, v[2:3], off nt
	v_lshl_add_u64 v[2:3], v[2:3], 0, s[60:61]
	global_load_dword v134, v[2:3], off nt
	v_lshl_add_u64 v[2:3], v[2:3], 0, s[60:61]
	global_load_dword v135, v[2:3], off nt
	v_lshl_add_u64 v[2:3], v[2:3], 0, s[60:61]
	s_waitcnt vmcnt(56)
; __device__ __forceinline__ float fsig(float x) { return __builtin_amdgcn_rcpf(1.0f + __builtin_amdgcn_exp2f(-1.4426950409f * x)); }
; __device__ __forceinline__ float fsilu(float x) { return x * fsig(x); }
; __global__ void __launch_bounds__(512, 2) fwd_megakernel(Params Parg) {
;     ...
;                 r -= NCONV; const int kc = r / 144, nc = r % 144, n = nc * 64 + lane;
;                 float a0 = 0.f, a1 = 0.f, a2 = 0.f;
;                 for (int k = kc * 128; k < kc * 128 + 128; ++k) { const float w = __builtin_nontemporal_load(&w_mod[(size_t)k * (NMOD * D) + n]); a0 += fsilu(cvec[k]) * w; a1 += fsilu(cvec[D + k]) * w; a2 += fsilu(cctx[k]) * w; }
	v_mul_f32_e32 v218, 0xbfb8aa3b, v211
	v_mul_f32_e32 v219, 0xbfb8aa3b, v212
	v_mul_f32_e32 v220, 0xbfb8aa3b, v214
	v_mul_f32_e32 v221, 0xbfb8aa3b, v215
	v_mul_f32_e32 v222, 0xbfb8aa3b, v216
	v_mul_f32_e32 v223, 0xbfb8aa3b, v217
	v_exp_f32_e32 v218, v218
	v_exp_f32_e32 v219, v219
	v_exp_f32_e32 v220, v220
	v_exp_f32_e32 v221, v221
	v_exp_f32_e32 v222, v222
	v_exp_f32_e32 v223, v223
	s_nop 0
	v_add_f32_e32 v218, 1.0, v218
	v_add_f32_e32 v219, 1.0, v219
	v_add_f32_e32 v220, 1.0, v220
	v_add_f32_e32 v221, 1.0, v221
	v_add_f32_e32 v222, 1.0, v222
	v_add_f32_e32 v223, 1.0, v223
	v_rcp_f32_e32 v218, v218
	v_rcp_f32_e32 v219, v219
	v_rcp_f32_e32 v220, v220
	v_rcp_f32_e32 v221, v221
	v_rcp_f32_e32 v222, v222
	v_rcp_f32_e32 v223, v223
	s_nop 0
	v_mul_f32_e32 v211, v211, v218
	v_mul_f32_e32 v212, v212, v219
	v_mul_f32_e32 v214, v214, v220
	v_mul_f32_e32 v215, v215, v221
	v_mul_f32_e32 v216, v216, v222
	v_mul_f32_e32 v217, v217, v223
	s_nop 1
	v_readlane_b32 s63, v211, 0
	v_readlane_b32 s64, v214, 0
	v_readlane_b32 s65, v216, 0
	s_waitcnt vmcnt(55)
	v_fmac_f32_e32 v4, s63, v80
	v_fmac_f32_e32 v5, s64, v80
	v_fmac_f32_e32 v29, s65, v80
	global_load_dword v80, v[2:3], off nt
	v_lshl_add_u64 v[2:3], v[2:3], 0, s[60:61]
	v_readlane_b32 s66, v211, 1
	v_readlane_b32 s67, v214, 1
	v_readlane_b32 s68, v216, 1
	s_waitcnt vmcnt(55)
	v_fmac_f32_e32 v4, s66, v81
	v_fmac_f32_e32 v5, s67, v81
	v_fmac_f32_e32 v29, s68, v81
	global_load_dword v81, v[2:3], off nt
	v_lshl_add_u64 v[2:3], v[2:3], 0, s[60:61]
	v_readlane_b32 s63, v211, 2
	v_readlane_b32 s64, v214, 2
	v_readlane_b32 s65, v216, 2
	s_waitcnt vmcnt(55)
	v_fmac_f32_e32 v4, s63, v82
	v_fmac_f32_e32 v5, s64, v82
	v_fmac_f32_e32 v29, s65, v82
	global_load_dword v82, v[2:3], off nt
	v_lshl_add_u64 v[2:3], v[2:3], 0, s[60:61]
	v_readlane_b32 s66, v211, 3
	v_readlane_b32 s67, v214, 3
	v_readlane_b32 s68, v216, 3
	s_waitcnt vmcnt(55)
	v_fmac_f32_e32 v4, s66, v83
	v_fmac_f32_e32 v5, s67, v83
	v_fmac_f32_e32 v29, s68, v83
	global_load_dword v83, v[2:3], off nt
	v_lshl_add_u64 v[2:3], v[2:3], 0, s[60:61]
	v_readlane_b32 s63, v211, 4
	v_readlane_b32 s64, v214, 4
	v_readlane_b32 s65, v216, 4
	s_waitcnt vmcnt(55)
	v_fmac_f32_e32 v4, s63, v84
	v_fmac_f32_e32 v5, s64, v84
	v_fmac_f32_e32 v29, s65, v84
	global_load_dword v84, v[2:3], off nt
	v_lshl_add_u64 v[2:3], v[2:3], 0, s[60:61]
	v_readlane_b32 s66, v211, 5
	v_readlane_b32 s67, v214, 5
	v_readlane_b32 s68, v216, 5
	s_waitcnt vmcnt(55)
	v_fmac_f32_e32 v4, s66, v85
	v_fmac_f32_e32 v5, s67, v85
	v_fmac_f32_e32 v29, s68, v85
	global_load_dword v85, v[2:3], off nt
	v_lshl_add_u64 v[2:3], v[2:3], 0, s[60:61]
	v_readlane_b32 s63, v211, 6
	v_readlane_b32 s64, v214, 6
	v_readlane_b32 s65, v216, 6
	s_waitcnt vmcnt(55)
	v_fmac_f32_e32 v4, s63, v86
	v_fmac_f32_e32 v5, s64, v86
	v_fmac_f32_e32 v29, s65, v86
	global_load_dword v86, v[2:3], off nt
	v_lshl_add_u64 v[2:3], v[2:3], 0, s[60:61]
	v_readlane_b32 s66, v211, 7
	v_readlane_b32 s67, v214, 7
	v_readlane_b32 s68, v216, 7
	s_waitcnt vmcnt(55)
	v_fmac_f32_e32 v4, s66, v87
	v_fmac_f32_e32 v5, s67, v87
	v_fmac_f32_e32 v29, s68, v87
	global_load_dword v87, v[2:3], off nt
	v_lshl_add_u64 v[2:3], v[2:3], 0, s[60:61]
	v_readlane_b32 s63, v211, 8
	v_readlane_b32 s64, v214, 8
	v_readlane_b32 s65, v216, 8
	s_waitcnt vmcnt(55)
	v_fmac_f32_e32 v4, s63, v88
	v_fmac_f32_e32 v5, s64, v88
	v_fmac_f32_e32 v29, s65, v88
	global_load_dword v88, v[2:3], off nt
	v_lshl_add_u64 v[2:3], v[2:3], 0, s[60:61]
	v_readlane_b32 s66, v211, 9
	v_readlane_b32 s67, v214, 9
	v_readlane_b32 s68, v216, 9
	s_waitcnt vmcnt(55)
	v_fmac_f32_e32 v4, s66, v89
	v_fmac_f32_e32 v5, s67, v89
	v_fmac_f32_e32 v29, s68, v89
	global_load_dword v89, v[2:3], off nt
	v_lshl_add_u64 v[2:3], v[2:3], 0, s[60:61]
	v_readlane_b32 s63, v211, 10
	v_readlane_b32 s64, v214, 10
	v_readlane_b32 s65, v216, 10
	s_waitcnt vmcnt(55)
	v_fmac_f32_e32 v4, s63, v90
	v_fmac_f32_e32 v5, s64, v90
	v_fmac_f32_e32 v29, s65, v90
	global_load_dword v90, v[2:3], off nt
	v_lshl_add_u64 v[2:3], v[2:3], 0, s[60:61]
	v_readlane_b32 s66, v211, 11
	v_readlane_b32 s67, v214, 11
	v_readlane_b32 s68, v216, 11
	s_waitcnt vmcnt(55)
	v_fmac_f32_e32 v4, s66, v91
	v_fmac_f32_e32 v5, s67, v91
	v_fmac_f32_e32 v29, s68, v91
	global_load_dword v91, v[2:3], off nt
	v_lshl_add_u64 v[2:3], v[2:3], 0, s[60:61]
	v_readlane_b32 s63, v211, 12
	v_readlane_b32 s64, v214, 12
	v_readlane_b32 s65, v216, 12
	s_waitcnt vmcnt(55)
	v_fmac_f32_e32 v4, s63, v92
	v_fmac_f32_e32 v5, s64, v92
	v_fmac_f32_e32 v29, s65, v92
	global_load_dword v92, v[2:3], off nt
	v_lshl_add_u64 v[2:3], v[2:3], 0, s[60:61]
	v_readlane_b32 s66, v211, 13
	v_readlane_b32 s67, v214, 13
	v_readlane_b32 s68, v216, 13
	s_waitcnt vmcnt(55)
	v_fmac_f32_e32 v4, s66, v93
	v_fmac_f32_e32 v5, s67, v93
	v_fmac_f32_e32 v29, s68, v93
	global_load_dword v93, v[2:3], off nt
	v_lshl_add_u64 v[2:3], v[2:3], 0, s[60:61]
	v_readlane_b32 s63, v211, 14
	v_readlane_b32 s64, v214, 14
	v_readlane_b32 s65, v216, 14
	s_waitcnt vmcnt(55)
	v_fmac_f32_e32 v4, s63, v94
	v_fmac_f32_e32 v5, s64, v94
	v_fmac_f32_e32 v29, s65, v94
	global_load_dword v94, v[2:3], off nt
	v_lshl_add_u64 v[2:3], v[2:3], 0, s[60:61]
	v_readlane_b32 s66, v211, 15
	v_readlane_b32 s67, v214, 15
	v_readlane_b32 s68, v216, 15
	s_waitcnt vmcnt(55)
	v_fmac_f32_e32 v4, s66, v95
	v_fmac_f32_e32 v5, s67, v95
	v_fmac_f32_e32 v29, s68, v95
	global_load_dword v95, v[2:3], off nt
	v_lshl_add_u64 v[2:3], v[2:3], 0, s[60:61]
	v_readlane_b32 s63, v211, 16
	v_readlane_b32 s64, v214, 16
	v_readlane_b32 s65, v216, 16
	s_waitcnt vmcnt(55)
; __device__ __forceinline__ float fsilu(float x) { return x * fsig(x); }
; __global__ void __launch_bounds__(512, 2) fwd_megakernel(Params Parg) {
;     ...
;                 float a0 = 0.f, a1 = 0.f, a2 = 0.f;
;                 for (int k = kc * 128; k < kc * 128 + 128; ++k) { const float w = __builtin_nontemporal_load(&w_mod[(size_t)k * (NMOD * D) + n]); a0 += fsilu(cvec[k]) * w; a1 += fsilu(cvec[D + k]) * w; a2 += fsilu(cctx[k]) * w; }
	v_fmac_f32_e32 v4, s63, v96
	v_fmac_f32_e32 v5, s64, v96
	v_fmac_f32_e32 v29, s65, v96
	global_load_dword v96, v[2:3], off nt
	v_lshl_add_u64 v[2:3], v[2:3], 0, s[60:61]
	v_readlane_b32 s66, v211, 17
	v_readlane_b32 s67, v214, 17
	v_readlane_b32 s68, v216, 17
	s_waitcnt vmcnt(55)
	v_fmac_f32_e32 v4, s66, v97
	v_fmac_f32_e32 v5, s67, v97
	v_fmac_f32_e32 v29, s68, v97
	global_load_dword v97, v[2:3], off nt
	v_lshl_add_u64 v[2:3], v[2:3], 0, s[60:61]
	v_readlane_b32 s63, v211, 18
	v_readlane_b32 s64, v214, 18
	v_readlane_b32 s65, v216, 18
	s_waitcnt vmcnt(55)
	v_fmac_f32_e32 v4, s63, v98
	v_fmac_f32_e32 v5, s64, v98
	v_fmac_f32_e32 v29, s65, v98
	global_load_dword v98, v[2:3], off nt
	v_lshl_add_u64 v[2:3], v[2:3], 0, s[60:61]
	v_readlane_b32 s66, v211, 19
	v_readlane_b32 s67, v214, 19
	v_readlane_b32 s68, v216, 19
	s_waitcnt vmcnt(55)
	v_fmac_f32_e32 v4, s66, v99
	v_fmac_f32_e32 v5, s67, v99
	v_fmac_f32_e32 v29, s68, v99
	global_load_dword v99, v[2:3], off nt
	v_lshl_add_u64 v[2:3], v[2:3], 0, s[60:61]
	v_readlane_b32 s63, v211, 20
	v_readlane_b32 s64, v214, 20
	v_readlane_b32 s65, v216, 20
	s_waitcnt vmcnt(55)
	v_fmac_f32_e32 v4, s63, v100
	v_fmac_f32_e32 v5, s64, v100
	v_fmac_f32_e32 v29, s65, v100
	global_load_dword v100, v[2:3], off nt
	v_lshl_add_u64 v[2:3], v[2:3], 0, s[60:61]
	v_readlane_b32 s66, v211, 21
	v_readlane_b32 s67, v214, 21
	v_readlane_b32 s68, v216, 21
	s_waitcnt vmcnt(55)
	v_fmac_f32_e32 v4, s66, v101
	v_fmac_f32_e32 v5, s67, v101
	v_fmac_f32_e32 v29, s68, v101
	global_load_dword v101, v[2:3], off nt
	v_lshl_add_u64 v[2:3], v[2:3], 0, s[60:61]
	v_readlane_b32 s63, v211, 22
	v_readlane_b32 s64, v214, 22
	v_readlane_b32 s65, v216, 22
	s_waitcnt vmcnt(55)
	v_fmac_f32_e32 v4, s63, v102
	v_fmac_f32_e32 v5, s64, v102
	v_fmac_f32_e32 v29, s65, v102
	global_load_dword v102, v[2:3], off nt
	v_lshl_add_u64 v[2:3], v[2:3], 0, s[60:61]
	v_readlane_b32 s66, v211, 23
	v_readlane_b32 s67, v214, 23
	v_readlane_b32 s68, v216, 23
	s_waitcnt vmcnt(55)
	v_fmac_f32_e32 v4, s66, v103
	v_fmac_f32_e32 v5, s67, v103
	v_fmac_f32_e32 v29, s68, v103
	global_load_dword v103, v[2:3], off nt
	v_lshl_add_u64 v[2:3], v[2:3], 0, s[60:61]
	v_readlane_b32 s63, v211, 24
	v_readlane_b32 s64, v214, 24
	v_readlane_b32 s65, v216, 24
	s_waitcnt vmcnt(55)
	v_fmac_f32_e32 v4, s63, v104
	v_fmac_f32_e32 v5, s64, v104
	v_fmac_f32_e32 v29, s65, v104
	global_load_dword v104, v[2:3], off nt
	v_lshl_add_u64 v[2:3], v[2:3], 0, s[60:61]
	v_readlane_b32 s66, v211, 25
	v_readlane_b32 s67, v214, 25
	v_readlane_b32 s68, v216, 25
	s_waitcnt vmcnt(55)
	v_fmac_f32_e32 v4, s66, v105
	v_fmac_f32_e32 v5, s67, v105
	v_fmac_f32_e32 v29, s68, v105
	global_load_dword v105, v[2:3], off nt
	v_lshl_add_u64 v[2:3], v[2:3], 0, s[60:61]
	v_readlane_b32 s63, v211, 26
	v_readlane_b32 s64, v214, 26
	v_readlane_b32 s65, v216, 26
	s_waitcnt vmcnt(55)
	v_fmac_f32_e32 v4, s63, v106
	v_fmac_f32_e32 v5, s64, v106
	v_fmac_f32_e32 v29, s65, v106
	global_load_dword v106, v[2:3], off nt
	v_lshl_add_u64 v[2:3], v[2:3], 0, s[60:61]
	v_readlane_b32 s66, v211, 27
	v_readlane_b32 s67, v214, 27
	v_readlane_b32 s68, v216, 27
	s_waitcnt vmcnt(55)
	v_fmac_f32_e32 v4, s66, v107
	v_fmac_f32_e32 v5, s67, v107
	v_fmac_f32_e32 v29, s68, v107
	global_load_dword v107, v[2:3], off nt
	v_lshl_add_u64 v[2:3], v[2:3], 0, s[60:61]
	v_readlane_b32 s63, v211, 28
	v_readlane_b32 s64, v214, 28
	v_readlane_b32 s65, v216, 28
	s_waitcnt vmcnt(55)
	v_fmac_f32_e32 v4, s63, v108
	v_fmac_f32_e32 v5, s64, v108
	v_fmac_f32_e32 v29, s65, v108
	global_load_dword v108, v[2:3], off nt
	v_lshl_add_u64 v[2:3], v[2:3], 0, s[60:61]
	v_readlane_b32 s66, v211, 29
	v_readlane_b32 s67, v214, 29
	v_readlane_b32 s68, v216, 29
	s_waitcnt vmcnt(55)
	v_fmac_f32_e32 v4, s66, v109
	v_fmac_f32_e32 v5, s67, v109
	v_fmac_f32_e32 v29, s68, v109
	global_load_dword v109, v[2:3], off nt
	v_lshl_add_u64 v[2:3], v[2:3], 0, s[60:61]
	v_readlane_b32 s63, v211, 30
	v_readlane_b32 s64, v214, 30
	v_readlane_b32 s65, v216, 30
	s_waitcnt vmcnt(55)
	v_fmac_f32_e32 v4, s63, v110
	v_fmac_f32_e32 v5, s64, v110
	v_fmac_f32_e32 v29, s65, v110
	global_load_dword v110, v[2:3], off nt
	v_lshl_add_u64 v[2:3], v[2:3], 0, s[60:61]
	v_readlane_b32 s66, v211, 31
	v_readlane_b32 s67, v214, 31
	v_readlane_b32 s68, v216, 31
	s_waitcnt vmcnt(55)
	v_fmac_f32_e32 v4, s66, v111
	v_fmac_f32_e32 v5, s67, v111
	v_fmac_f32_e32 v29, s68, v111
	global_load_dword v111, v[2:3], off nt
	v_lshl_add_u64 v[2:3], v[2:3], 0, s[60:61]
	v_readlane_b32 s63, v211, 32
	v_readlane_b32 s64, v214, 32
	v_readlane_b32 s65, v216, 32
	s_waitcnt vmcnt(55)
	v_fmac_f32_e32 v4, s63, v112
	v_fmac_f32_e32 v5, s64, v112
	v_fmac_f32_e32 v29, s65, v112
	global_load_dword v112, v[2:3], off nt
	v_lshl_add_u64 v[2:3], v[2:3], 0, s[60:61]
	v_readlane_b32 s66, v211, 33
	v_readlane_b32 s67, v214, 33
	v_readlane_b32 s68, v216, 33
	s_waitcnt vmcnt(55)
	v_fmac_f32_e32 v4, s66, v113
	v_fmac_f32_e32 v5, s67, v113
	v_fmac_f32_e32 v29, s68, v113
	global_load_dword v113, v[2:3], off nt
	v_lshl_add_u64 v[2:3], v[2:3], 0, s[60:61]
	v_readlane_b32 s63, v211, 34
	v_readlane_b32 s64, v214, 34
	v_readlane_b32 s65, v216, 34
	s_waitcnt vmcnt(55)
	v_fmac_f32_e32 v4, s63, v114
	v_fmac_f32_e32 v5, s64, v114
	v_fmac_f32_e32 v29, s65, v114
	global_load_dword v114, v[2:3], off nt
	v_lshl_add_u64 v[2:3], v[2:3], 0, s[60:61]
	v_readlane_b32 s66, v211, 35
	v_readlane_b32 s67, v214, 35
	v_readlane_b32 s68, v216, 35
	s_waitcnt vmcnt(55)
	v_fmac_f32_e32 v4, s66, v115
	v_fmac_f32_e32 v5, s67, v115
	v_fmac_f32_e32 v29, s68, v115
	global_load_dword v115, v[2:3], off nt
	v_lshl_add_u64 v[2:3], v[2:3], 0, s[60:61]
	v_readlane_b32 s63, v211, 36
	v_readlane_b32 s64, v214, 36
	v_readlane_b32 s65, v216, 36
	s_waitcnt vmcnt(55)
; __device__ __forceinline__ float fsilu(float x) { return x * fsig(x); }
; __global__ void __launch_bounds__(512, 2) fwd_megakernel(Params Parg) {
;     ...
;                 float a0 = 0.f, a1 = 0.f, a2 = 0.f;
;                 for (int k = kc * 128; k < kc * 128 + 128; ++k) { const float w = __builtin_nontemporal_load(&w_mod[(size_t)k * (NMOD * D) + n]); a0 += fsilu(cvec[k]) * w; a1 += fsilu(cvec[D + k]) * w; a2 += fsilu(cctx[k]) * w; }
	v_fmac_f32_e32 v4, s63, v116
	v_fmac_f32_e32 v5, s64, v116
	v_fmac_f32_e32 v29, s65, v116
	global_load_dword v116, v[2:3], off nt
	v_lshl_add_u64 v[2:3], v[2:3], 0, s[60:61]
	v_readlane_b32 s66, v211, 37
	v_readlane_b32 s67, v214, 37
	v_readlane_b32 s68, v216, 37
	s_waitcnt vmcnt(55)
	v_fmac_f32_e32 v4, s66, v117
	v_fmac_f32_e32 v5, s67, v117
	v_fmac_f32_e32 v29, s68, v117
	global_load_dword v117, v[2:3], off nt
	v_lshl_add_u64 v[2:3], v[2:3], 0, s[60:61]
	v_readlane_b32 s63, v211, 38
	v_readlane_b32 s64, v214, 38
	v_readlane_b32 s65, v216, 38
	s_waitcnt vmcnt(55)
	v_fmac_f32_e32 v4, s63, v118
	v_fmac_f32_e32 v5, s64, v118
	v_fmac_f32_e32 v29, s65, v118
	global_load_dword v118, v[2:3], off nt
	v_lshl_add_u64 v[2:3], v[2:3], 0, s[60:61]
	v_readlane_b32 s66, v211, 39
	v_readlane_b32 s67, v214, 39
	v_readlane_b32 s68, v216, 39
	s_waitcnt vmcnt(55)
	v_fmac_f32_e32 v4, s66, v119
	v_fmac_f32_e32 v5, s67, v119
	v_fmac_f32_e32 v29, s68, v119
	global_load_dword v119, v[2:3], off nt
	v_lshl_add_u64 v[2:3], v[2:3], 0, s[60:61]
	v_readlane_b32 s63, v211, 40
	v_readlane_b32 s64, v214, 40
	v_readlane_b32 s65, v216, 40
	s_waitcnt vmcnt(55)
	v_fmac_f32_e32 v4, s63, v120
	v_fmac_f32_e32 v5, s64, v120
	v_fmac_f32_e32 v29, s65, v120
	global_load_dword v120, v[2:3], off nt
	v_lshl_add_u64 v[2:3], v[2:3], 0, s[60:61]
	v_readlane_b32 s66, v211, 41
	v_readlane_b32 s67, v214, 41
	v_readlane_b32 s68, v216, 41
	s_waitcnt vmcnt(55)
	v_fmac_f32_e32 v4, s66, v121
	v_fmac_f32_e32 v5, s67, v121
	v_fmac_f32_e32 v29, s68, v121
	global_load_dword v121, v[2:3], off nt
	v_lshl_add_u64 v[2:3], v[2:3], 0, s[60:61]
	v_readlane_b32 s63, v211, 42
	v_readlane_b32 s64, v214, 42
	v_readlane_b32 s65, v216, 42
	s_waitcnt vmcnt(55)
	v_fmac_f32_e32 v4, s63, v122
	v_fmac_f32_e32 v5, s64, v122
	v_fmac_f32_e32 v29, s65, v122
	global_load_dword v122, v[2:3], off nt
	v_lshl_add_u64 v[2:3], v[2:3], 0, s[60:61]
	v_readlane_b32 s66, v211, 43
	v_readlane_b32 s67, v214, 43
	v_readlane_b32 s68, v216, 43
	s_waitcnt vmcnt(55)
	v_fmac_f32_e32 v4, s66, v123
	v_fmac_f32_e32 v5, s67, v123
	v_fmac_f32_e32 v29, s68, v123
	global_load_dword v123, v[2:3], off nt
	v_lshl_add_u64 v[2:3], v[2:3], 0, s[60:61]
	v_readlane_b32 s63, v211, 44
	v_readlane_b32 s64, v214, 44
	v_readlane_b32 s65, v216, 44
	s_waitcnt vmcnt(55)
	v_fmac_f32_e32 v4, s63, v124
	v_fmac_f32_e32 v5, s64, v124
	v_fmac_f32_e32 v29, s65, v124
	global_load_dword v124, v[2:3], off nt
	v_lshl_add_u64 v[2:3], v[2:3], 0, s[60:61]
	v_readlane_b32 s66, v211, 45
	v_readlane_b32 s67, v214, 45
	v_readlane_b32 s68, v216, 45
	s_waitcnt vmcnt(55)
	v_fmac_f32_e32 v4, s66, v125
	v_fmac_f32_e32 v5, s67, v125
	v_fmac_f32_e32 v29, s68, v125
	global_load_dword v125, v[2:3], off nt
	v_lshl_add_u64 v[2:3], v[2:3], 0, s[60:61]
	v_readlane_b32 s63, v211, 46
	v_readlane_b32 s64, v214, 46
	v_readlane_b32 s65, v216, 46
	s_waitcnt vmcnt(55)
	v_fmac_f32_e32 v4, s63, v126
	v_fmac_f32_e32 v5, s64, v126
	v_fmac_f32_e32 v29, s65, v126
	global_load_dword v126, v[2:3], off nt
	v_lshl_add_u64 v[2:3], v[2:3], 0, s[60:61]
	v_readlane_b32 s66, v211, 47
	v_readlane_b32 s67, v214, 47
	v_readlane_b32 s68, v216, 47
	s_waitcnt vmcnt(55)
	v_fmac_f32_e32 v4, s66, v127
	v_fmac_f32_e32 v5, s67, v127
	v_fmac_f32_e32 v29, s68, v127
	global_load_dword v127, v[2:3], off nt
	v_lshl_add_u64 v[2:3], v[2:3], 0, s[60:61]
	v_readlane_b32 s63, v211, 48
	v_readlane_b32 s64, v214, 48
	v_readlane_b32 s65, v216, 48
	s_waitcnt vmcnt(55)
	v_fmac_f32_e32 v4, s63, v128
	v_fmac_f32_e32 v5, s64, v128
	v_fmac_f32_e32 v29, s65, v128
	global_load_dword v128, v[2:3], off nt
	v_lshl_add_u64 v[2:3], v[2:3], 0, s[60:61]
	v_readlane_b32 s66, v211, 49
	v_readlane_b32 s67, v214, 49
	v_readlane_b32 s68, v216, 49
	s_waitcnt vmcnt(55)
	v_fmac_f32_e32 v4, s66, v129
	v_fmac_f32_e32 v5, s67, v129
	v_fmac_f32_e32 v29, s68, v129
	global_load_dword v129, v[2:3], off nt
	v_lshl_add_u64 v[2:3], v[2:3], 0, s[60:61]
	v_readlane_b32 s63, v211, 50
	v_readlane_b32 s64, v214, 50
	v_readlane_b32 s65, v216, 50
	s_waitcnt vmcnt(55)
	v_fmac_f32_e32 v4, s63, v130
	v_fmac_f32_e32 v5, s64, v130
	v_fmac_f32_e32 v29, s65, v130
	global_load_dword v130, v[2:3], off nt
	v_lshl_add_u64 v[2:3], v[2:3], 0, s[60:61]
	v_readlane_b32 s66, v211, 51
	v_readlane_b32 s67, v214, 51
	v_readlane_b32 s68, v216, 51
	s_waitcnt vmcnt(55)
	v_fmac_f32_e32 v4, s66, v131
	v_fmac_f32_e32 v5, s67, v131
	v_fmac_f32_e32 v29, s68, v131
	global_load_dword v131, v[2:3], off nt
	v_lshl_add_u64 v[2:3], v[2:3], 0, s[60:61]
	v_readlane_b32 s63, v211, 52
	v_readlane_b32 s64, v214, 52
	v_readlane_b32 s65, v216, 52
	s_waitcnt vmcnt(55)
	v_fmac_f32_e32 v4, s63, v132
	v_fmac_f32_e32 v5, s64, v132
	v_fmac_f32_e32 v29, s65, v132
	global_load_dword v132, v[2:3], off nt
	v_lshl_add_u64 v[2:3], v[2:3], 0, s[60:61]
	v_readlane_b32 s66, v211, 53
	v_readlane_b32 s67, v214, 53
	v_readlane_b32 s68, v216, 53
	s_waitcnt vmcnt(55)
	v_fmac_f32_e32 v4, s66, v133
	v_fmac_f32_e32 v5, s67, v133
	v_fmac_f32_e32 v29, s68, v133
	global_load_dword v133, v[2:3], off nt
	v_lshl_add_u64 v[2:3], v[2:3], 0, s[60:61]
	v_readlane_b32 s63, v211, 54
	v_readlane_b32 s64, v214, 54
	v_readlane_b32 s65, v216, 54
	s_waitcnt vmcnt(55)
	v_fmac_f32_e32 v4, s63, v134
	v_fmac_f32_e32 v5, s64, v134
	v_fmac_f32_e32 v29, s65, v134
	global_load_dword v134, v[2:3], off nt
	v_lshl_add_u64 v[2:3], v[2:3], 0, s[60:61]
	v_readlane_b32 s66, v211, 55
	v_readlane_b32 s67, v214, 55
	v_readlane_b32 s68, v216, 55
	s_waitcnt vmcnt(55)
	v_fmac_f32_e32 v4, s66, v135
	v_fmac_f32_e32 v5, s67, v135
	v_fmac_f32_e32 v29, s68, v135
	global_load_dword v135, v[2:3], off nt
	v_lshl_add_u64 v[2:3], v[2:3], 0, s[60:61]
	v_readlane_b32 s63, v211, 56
	v_readlane_b32 s64, v214, 56
	v_readlane_b32 s65, v216, 56
	s_waitcnt vmcnt(55)
; __device__ __forceinline__ float fsilu(float x) { return x * fsig(x); }
; __global__ void __launch_bounds__(512, 2) fwd_megakernel(Params Parg) {
;     ...
;                 float a0 = 0.f, a1 = 0.f, a2 = 0.f;
;                 for (int k = kc * 128; k < kc * 128 + 128; ++k) { const float w = __builtin_nontemporal_load(&w_mod[(size_t)k * (NMOD * D) + n]); a0 += fsilu(cvec[k]) * w; a1 += fsilu(cvec[D + k]) * w; a2 += fsilu(cctx[k]) * w; }
	v_fmac_f32_e32 v4, s63, v80
	v_fmac_f32_e32 v5, s64, v80
	v_fmac_f32_e32 v29, s65, v80
	global_load_dword v80, v[2:3], off nt
	v_lshl_add_u64 v[2:3], v[2:3], 0, s[60:61]
	v_readlane_b32 s66, v211, 57
	v_readlane_b32 s67, v214, 57
	v_readlane_b32 s68, v216, 57
	s_waitcnt vmcnt(55)
	v_fmac_f32_e32 v4, s66, v81
	v_fmac_f32_e32 v5, s67, v81
	v_fmac_f32_e32 v29, s68, v81
	global_load_dword v81, v[2:3], off nt
	v_lshl_add_u64 v[2:3], v[2:3], 0, s[60:61]
	v_readlane_b32 s63, v211, 58
	v_readlane_b32 s64, v214, 58
	v_readlane_b32 s65, v216, 58
	s_waitcnt vmcnt(55)
	v_fmac_f32_e32 v4, s63, v82
	v_fmac_f32_e32 v5, s64, v82
	v_fmac_f32_e32 v29, s65, v82
	global_load_dword v82, v[2:3], off nt
	v_lshl_add_u64 v[2:3], v[2:3], 0, s[60:61]
	v_readlane_b32 s66, v211, 59
	v_readlane_b32 s67, v214, 59
	v_readlane_b32 s68, v216, 59
	s_waitcnt vmcnt(55)
	v_fmac_f32_e32 v4, s66, v83
	v_fmac_f32_e32 v5, s67, v83
	v_fmac_f32_e32 v29, s68, v83
	global_load_dword v83, v[2:3], off nt
	v_lshl_add_u64 v[2:3], v[2:3], 0, s[60:61]
	v_readlane_b32 s63, v211, 60
	v_readlane_b32 s64, v214, 60
	v_readlane_b32 s65, v216, 60
	s_waitcnt vmcnt(55)
	v_fmac_f32_e32 v4, s63, v84
	v_fmac_f32_e32 v5, s64, v84
	v_fmac_f32_e32 v29, s65, v84
	global_load_dword v84, v[2:3], off nt
	v_lshl_add_u64 v[2:3], v[2:3], 0, s[60:61]
	v_readlane_b32 s66, v211, 61
	v_readlane_b32 s67, v214, 61
	v_readlane_b32 s68, v216, 61
	s_waitcnt vmcnt(55)
	v_fmac_f32_e32 v4, s66, v85
	v_fmac_f32_e32 v5, s67, v85
	v_fmac_f32_e32 v29, s68, v85
	global_load_dword v85, v[2:3], off nt
	v_lshl_add_u64 v[2:3], v[2:3], 0, s[60:61]
	v_readlane_b32 s63, v211, 62
	v_readlane_b32 s64, v214, 62
	v_readlane_b32 s65, v216, 62
	s_waitcnt vmcnt(55)
	v_fmac_f32_e32 v4, s63, v86
	v_fmac_f32_e32 v5, s64, v86
	v_fmac_f32_e32 v29, s65, v86
	global_load_dword v86, v[2:3], off nt
	v_lshl_add_u64 v[2:3], v[2:3], 0, s[60:61]
	v_readlane_b32 s66, v211, 63
	v_readlane_b32 s67, v214, 63
	v_readlane_b32 s68, v216, 63
	s_waitcnt vmcnt(55)
	v_fmac_f32_e32 v4, s66, v87
	v_fmac_f32_e32 v5, s67, v87
	v_fmac_f32_e32 v29, s68, v87
	global_load_dword v87, v[2:3], off nt
	v_lshl_add_u64 v[2:3], v[2:3], 0, s[60:61]
	v_readlane_b32 s63, v212, 0
	v_readlane_b32 s64, v215, 0
	v_readlane_b32 s65, v217, 0
	s_waitcnt vmcnt(55)
	v_fmac_f32_e32 v4, s63, v88
	v_fmac_f32_e32 v5, s64, v88
	v_fmac_f32_e32 v29, s65, v88
	global_load_dword v88, v[2:3], off nt
	v_lshl_add_u64 v[2:3], v[2:3], 0, s[60:61]
	v_readlane_b32 s66, v212, 1
	v_readlane_b32 s67, v215, 1
	v_readlane_b32 s68, v217, 1
	s_waitcnt vmcnt(55)
	v_fmac_f32_e32 v4, s66, v89
	v_fmac_f32_e32 v5, s67, v89
	v_fmac_f32_e32 v29, s68, v89
	global_load_dword v89, v[2:3], off nt
	v_lshl_add_u64 v[2:3], v[2:3], 0, s[60:61]
	v_readlane_b32 s63, v212, 2
	v_readlane_b32 s64, v215, 2
	v_readlane_b32 s65, v217, 2
	s_waitcnt vmcnt(55)
	v_fmac_f32_e32 v4, s63, v90
	v_fmac_f32_e32 v5, s64, v90
	v_fmac_f32_e32 v29, s65, v90
	global_load_dword v90, v[2:3], off nt
	v_lshl_add_u64 v[2:3], v[2:3], 0, s[60:61]
	v_readlane_b32 s66, v212, 3
	v_readlane_b32 s67, v215, 3
	v_readlane_b32 s68, v217, 3
	s_waitcnt vmcnt(55)
	v_fmac_f32_e32 v4, s66, v91
	v_fmac_f32_e32 v5, s67, v91
	v_fmac_f32_e32 v29, s68, v91
	global_load_dword v91, v[2:3], off nt
	v_lshl_add_u64 v[2:3], v[2:3], 0, s[60:61]
	v_readlane_b32 s63, v212, 4
	v_readlane_b32 s64, v215, 4
	v_readlane_b32 s65, v217, 4
	s_waitcnt vmcnt(55)
	v_fmac_f32_e32 v4, s63, v92
	v_fmac_f32_e32 v5, s64, v92
	v_fmac_f32_e32 v29, s65, v92
	global_load_dword v92, v[2:3], off nt
	v_lshl_add_u64 v[2:3], v[2:3], 0, s[60:61]
	v_readlane_b32 s66, v212, 5
	v_readlane_b32 s67, v215, 5
	v_readlane_b32 s68, v217, 5
	s_waitcnt vmcnt(55)
	v_fmac_f32_e32 v4, s66, v93
	v_fmac_f32_e32 v5, s67, v93
	v_fmac_f32_e32 v29, s68, v93
	global_load_dword v93, v[2:3], off nt
	v_lshl_add_u64 v[2:3], v[2:3], 0, s[60:61]
	v_readlane_b32 s63, v212, 6
	v_readlane_b32 s64, v215, 6
	v_readlane_b32 s65, v217, 6
	s_waitcnt vmcnt(55)
	v_fmac_f32_e32 v4, s63, v94
	v_fmac_f32_e32 v5, s64, v94
	v_fmac_f32_e32 v29, s65, v94
	global_load_dword v94, v[2:3], off nt
	v_lshl_add_u64 v[2:3], v[2:3], 0, s[60:61]
	v_readlane_b32 s66, v212, 7
	v_readlane_b32 s67, v215, 7
	v_readlane_b32 s68, v217, 7
	s_waitcnt vmcnt(55)
	v_fmac_f32_e32 v4, s66, v95
	v_fmac_f32_e32 v5, s67, v95
	v_fmac_f32_e32 v29, s68, v95
	global_load_dword v95, v[2:3], off nt
	v_lshl_add_u64 v[2:3], v[2:3], 0, s[60:61]
	v_readlane_b32 s63, v212, 8
	v_readlane_b32 s64, v215, 8
	v_readlane_b32 s65, v217, 8
	s_waitcnt vmcnt(55)
	v_fmac_f32_e32 v4, s63, v96
	v_fmac_f32_e32 v5, s64, v96
	v_fmac_f32_e32 v29, s65, v96
	v_readlane_b32 s66, v212, 9
	v_readlane_b32 s67, v215, 9
	v_readlane_b32 s68, v217, 9
	s_waitcnt vmcnt(54)
	v_fmac_f32_e32 v4, s66, v97
	v_fmac_f32_e32 v5, s67, v97
	v_fmac_f32_e32 v29, s68, v97
	v_readlane_b32 s63, v212, 10
	v_readlane_b32 s64, v215, 10
	v_readlane_b32 s65, v217, 10
	s_waitcnt vmcnt(53)
	v_fmac_f32_e32 v4, s63, v98
	v_fmac_f32_e32 v5, s64, v98
	v_fmac_f32_e32 v29, s65, v98
	v_readlane_b32 s66, v212, 11
	v_readlane_b32 s67, v215, 11
	v_readlane_b32 s68, v217, 11
	s_waitcnt vmcnt(52)
	v_fmac_f32_e32 v4, s66, v99
	v_fmac_f32_e32 v5, s67, v99
	v_fmac_f32_e32 v29, s68, v99
	v_readlane_b32 s63, v212, 12
	v_readlane_b32 s64, v215, 12
	v_readlane_b32 s65, v217, 12
	s_waitcnt vmcnt(51)
	v_fmac_f32_e32 v4, s63, v100
	v_fmac_f32_e32 v5, s64, v100
	v_fmac_f32_e32 v29, s65, v100
	v_readlane_b32 s66, v212, 13
	v_readlane_b32 s67, v215, 13
	v_readlane_b32 s68, v217, 13
	s_waitcnt vmcnt(50)
	v_fmac_f32_e32 v4, s66, v101
	v_fmac_f32_e32 v5, s67, v101
	v_fmac_f32_e32 v29, s68, v101
	v_readlane_b32 s63, v212, 14
	v_readlane_b32 s64, v215, 14
	v_readlane_b32 s65, v217, 14
	s_waitcnt vmcnt(49)
; __device__ __forceinline__ float fsilu(float x) { return x * fsig(x); }
; __global__ void __launch_bounds__(512, 2) fwd_megakernel(Params Parg) {
;     ...
;                 float a0 = 0.f, a1 = 0.f, a2 = 0.f;
;                 for (int k = kc * 128; k < kc * 128 + 128; ++k) { const float w = __builtin_nontemporal_load(&w_mod[(size_t)k * (NMOD * D) + n]); a0 += fsilu(cvec[k]) * w; a1 += fsilu(cvec[D + k]) * w; a2 += fsilu(cctx[k]) * w; }
	v_fmac_f32_e32 v4, s63, v102
	v_fmac_f32_e32 v5, s64, v102
	v_fmac_f32_e32 v29, s65, v102
	v_readlane_b32 s66, v212, 15
	v_readlane_b32 s67, v215, 15
	v_readlane_b32 s68, v217, 15
	s_waitcnt vmcnt(48)
	v_fmac_f32_e32 v4, s66, v103
	v_fmac_f32_e32 v5, s67, v103
	v_fmac_f32_e32 v29, s68, v103
	v_readlane_b32 s63, v212, 16
	v_readlane_b32 s64, v215, 16
	v_readlane_b32 s65, v217, 16
	s_waitcnt vmcnt(47)
	v_fmac_f32_e32 v4, s63, v104
	v_fmac_f32_e32 v5, s64, v104
	v_fmac_f32_e32 v29, s65, v104
	v_readlane_b32 s66, v212, 17
	v_readlane_b32 s67, v215, 17
	v_readlane_b32 s68, v217, 17
	s_waitcnt vmcnt(46)
	v_fmac_f32_e32 v4, s66, v105
	v_fmac_f32_e32 v5, s67, v105
	v_fmac_f32_e32 v29, s68, v105
	v_readlane_b32 s63, v212, 18
	v_readlane_b32 s64, v215, 18
	v_readlane_b32 s65, v217, 18
	s_waitcnt vmcnt(45)
	v_fmac_f32_e32 v4, s63, v106
	v_fmac_f32_e32 v5, s64, v106
	v_fmac_f32_e32 v29, s65, v106
	v_readlane_b32 s66, v212, 19
	v_readlane_b32 s67, v215, 19
	v_readlane_b32 s68, v217, 19
	s_waitcnt vmcnt(44)
	v_fmac_f32_e32 v4, s66, v107
	v_fmac_f32_e32 v5, s67, v107
	v_fmac_f32_e32 v29, s68, v107
	v_readlane_b32 s63, v212, 20
	v_readlane_b32 s64, v215, 20
	v_readlane_b32 s65, v217, 20
	s_waitcnt vmcnt(43)
	v_fmac_f32_e32 v4, s63, v108
	v_fmac_f32_e32 v5, s64, v108
	v_fmac_f32_e32 v29, s65, v108
	v_readlane_b32 s66, v212, 21
	v_readlane_b32 s67, v215, 21
	v_readlane_b32 s68, v217, 21
	s_waitcnt vmcnt(42)
	v_fmac_f32_e32 v4, s66, v109
	v_fmac_f32_e32 v5, s67, v109
	v_fmac_f32_e32 v29, s68, v109
	v_readlane_b32 s63, v212, 22
	v_readlane_b32 s64, v215, 22
	v_readlane_b32 s65, v217, 22
	s_waitcnt vmcnt(41)
	v_fmac_f32_e32 v4, s63, v110
	v_fmac_f32_e32 v5, s64, v110
	v_fmac_f32_e32 v29, s65, v110
	v_readlane_b32 s66, v212, 23
	v_readlane_b32 s67, v215, 23
	v_readlane_b32 s68, v217, 23
	s_waitcnt vmcnt(40)
	v_fmac_f32_e32 v4, s66, v111
	v_fmac_f32_e32 v5, s67, v111
	v_fmac_f32_e32 v29, s68, v111
	v_readlane_b32 s63, v212, 24
	v_readlane_b32 s64, v215, 24
	v_readlane_b32 s65, v217, 24
	s_waitcnt vmcnt(39)
	v_fmac_f32_e32 v4, s63, v112
	v_fmac_f32_e32 v5, s64, v112
	v_fmac_f32_e32 v29, s65, v112
	v_readlane_b32 s66, v212, 25
	v_readlane_b32 s67, v215, 25
	v_readlane_b32 s68, v217, 25
	s_waitcnt vmcnt(38)
	v_fmac_f32_e32 v4, s66, v113
	v_fmac_f32_e32 v5, s67, v113
	v_fmac_f32_e32 v29, s68, v113
	v_readlane_b32 s63, v212, 26
	v_readlane_b32 s64, v215, 26
	v_readlane_b32 s65, v217, 26
	s_waitcnt vmcnt(37)
	v_fmac_f32_e32 v4, s63, v114
	v_fmac_f32_e32 v5, s64, v114
	v_fmac_f32_e32 v29, s65, v114
	v_readlane_b32 s66, v212, 27
	v_readlane_b32 s67, v215, 27
	v_readlane_b32 s68, v217, 27
	s_waitcnt vmcnt(36)
	v_fmac_f32_e32 v4, s66, v115
	v_fmac_f32_e32 v5, s67, v115
	v_fmac_f32_e32 v29, s68, v115
	v_readlane_b32 s63, v212, 28
	v_readlane_b32 s64, v215, 28
	v_readlane_b32 s65, v217, 28
	s_waitcnt vmcnt(35)
	v_fmac_f32_e32 v4, s63, v116
	v_fmac_f32_e32 v5, s64, v116
	v_fmac_f32_e32 v29, s65, v116
	v_readlane_b32 s66, v212, 29
	v_readlane_b32 s67, v215, 29
	v_readlane_b32 s68, v217, 29
	s_waitcnt vmcnt(34)
	v_fmac_f32_e32 v4, s66, v117
	v_fmac_f32_e32 v5, s67, v117
	v_fmac_f32_e32 v29, s68, v117
	v_readlane_b32 s63, v212, 30
	v_readlane_b32 s64, v215, 30
	v_readlane_b32 s65, v217, 30
	s_waitcnt vmcnt(33)
	v_fmac_f32_e32 v4, s63, v118
	v_fmac_f32_e32 v5, s64, v118
	v_fmac_f32_e32 v29, s65, v118
	v_readlane_b32 s66, v212, 31
	v_readlane_b32 s67, v215, 31
	v_readlane_b32 s68, v217, 31
	s_waitcnt vmcnt(32)
	v_fmac_f32_e32 v4, s66, v119
	v_fmac_f32_e32 v5, s67, v119
	v_fmac_f32_e32 v29, s68, v119
	v_readlane_b32 s63, v212, 32
	v_readlane_b32 s64, v215, 32
	v_readlane_b32 s65, v217, 32
	s_waitcnt vmcnt(31)
	v_fmac_f32_e32 v4, s63, v120
	v_fmac_f32_e32 v5, s64, v120
	v_fmac_f32_e32 v29, s65, v120
	v_readlane_b32 s66, v212, 33
	v_readlane_b32 s67, v215, 33
	v_readlane_b32 s68, v217, 33
	s_waitcnt vmcnt(30)
	v_fmac_f32_e32 v4, s66, v121
	v_fmac_f32_e32 v5, s67, v121
	v_fmac_f32_e32 v29, s68, v121
	v_readlane_b32 s63, v212, 34
	v_readlane_b32 s64, v215, 34
	v_readlane_b32 s65, v217, 34
	s_waitcnt vmcnt(29)
	v_fmac_f32_e32 v4, s63, v122
	v_fmac_f32_e32 v5, s64, v122
	v_fmac_f32_e32 v29, s65, v122
	v_readlane_b32 s66, v212, 35
	v_readlane_b32 s67, v215, 35
	v_readlane_b32 s68, v217, 35
	s_waitcnt vmcnt(28)
	v_fmac_f32_e32 v4, s66, v123
	v_fmac_f32_e32 v5, s67, v123
	v_fmac_f32_e32 v29, s68, v123
	v_readlane_b32 s63, v212, 36
	v_readlane_b32 s64, v215, 36
	v_readlane_b32 s65, v217, 36
	s_waitcnt vmcnt(27)
	v_fmac_f32_e32 v4, s63, v124
	v_fmac_f32_e32 v5, s64, v124
	v_fmac_f32_e32 v29, s65, v124
	v_readlane_b32 s66, v212, 37
	v_readlane_b32 s67, v215, 37
	v_readlane_b32 s68, v217, 37
	s_waitcnt vmcnt(26)
	v_fmac_f32_e32 v4, s66, v125
	v_fmac_f32_e32 v5, s67, v125
	v_fmac_f32_e32 v29, s68, v125
	v_readlane_b32 s63, v212, 38
	v_readlane_b32 s64, v215, 38
	v_readlane_b32 s65, v217, 38
	s_waitcnt vmcnt(25)
	v_fmac_f32_e32 v4, s63, v126
	v_fmac_f32_e32 v5, s64, v126
	v_fmac_f32_e32 v29, s65, v126
	v_readlane_b32 s66, v212, 39
	v_readlane_b32 s67, v215, 39
	v_readlane_b32 s68, v217, 39
	s_waitcnt vmcnt(24)
	v_fmac_f32_e32 v4, s66, v127
	v_fmac_f32_e32 v5, s67, v127
	v_fmac_f32_e32 v29, s68, v127
	v_readlane_b32 s63, v212, 40
	v_readlane_b32 s64, v215, 40
	v_readlane_b32 s65, v217, 40
	s_waitcnt vmcnt(23)
; __device__ __forceinline__ float fsilu(float x) { return x * fsig(x); }
; __global__ void __launch_bounds__(512, 2) fwd_megakernel(Params Parg) {
;     ...
;                 float a0 = 0.f, a1 = 0.f, a2 = 0.f;
;                 for (int k = kc * 128; k < kc * 128 + 128; ++k) { const float w = __builtin_nontemporal_load(&w_mod[(size_t)k * (NMOD * D) + n]); a0 += fsilu(cvec[k]) * w; a1 += fsilu(cvec[D + k]) * w; a2 += fsilu(cctx[k]) * w; }
;                 part[(kc * 3 + 0) * (NMOD * D) + n] = a0; part[(kc * 3 + 1) * (NMOD * D) + n] = a1; part[(kc * 3 + 2) * (NMOD * D) + n] = a2;
;                 continue;
	v_fmac_f32_e32 v4, s63, v128
	v_fmac_f32_e32 v5, s64, v128
	v_fmac_f32_e32 v29, s65, v128
	v_readlane_b32 s66, v212, 41
	v_readlane_b32 s67, v215, 41
	v_readlane_b32 s68, v217, 41
	s_waitcnt vmcnt(22)
	v_fmac_f32_e32 v4, s66, v129
	v_fmac_f32_e32 v5, s67, v129
	v_fmac_f32_e32 v29, s68, v129
	v_readlane_b32 s63, v212, 42
	v_readlane_b32 s64, v215, 42
	v_readlane_b32 s65, v217, 42
	s_waitcnt vmcnt(21)
	v_fmac_f32_e32 v4, s63, v130
	v_fmac_f32_e32 v5, s64, v130
	v_fmac_f32_e32 v29, s65, v130
	v_readlane_b32 s66, v212, 43
	v_readlane_b32 s67, v215, 43
	v_readlane_b32 s68, v217, 43
	s_waitcnt vmcnt(20)
	v_fmac_f32_e32 v4, s66, v131
	v_fmac_f32_e32 v5, s67, v131
	v_fmac_f32_e32 v29, s68, v131
	v_readlane_b32 s63, v212, 44
	v_readlane_b32 s64, v215, 44
	v_readlane_b32 s65, v217, 44
	s_waitcnt vmcnt(19)
	v_fmac_f32_e32 v4, s63, v132
	v_fmac_f32_e32 v5, s64, v132
	v_fmac_f32_e32 v29, s65, v132
	v_readlane_b32 s66, v212, 45
	v_readlane_b32 s67, v215, 45
	v_readlane_b32 s68, v217, 45
	s_waitcnt vmcnt(18)
	v_fmac_f32_e32 v4, s66, v133
	v_fmac_f32_e32 v5, s67, v133
	v_fmac_f32_e32 v29, s68, v133
	v_readlane_b32 s63, v212, 46
	v_readlane_b32 s64, v215, 46
	v_readlane_b32 s65, v217, 46
	s_waitcnt vmcnt(17)
	v_fmac_f32_e32 v4, s63, v134
	v_fmac_f32_e32 v5, s64, v134
	v_fmac_f32_e32 v29, s65, v134
	v_readlane_b32 s66, v212, 47
	v_readlane_b32 s67, v215, 47
	v_readlane_b32 s68, v217, 47
	s_waitcnt vmcnt(16)
	v_fmac_f32_e32 v4, s66, v135
	v_fmac_f32_e32 v5, s67, v135
	v_fmac_f32_e32 v29, s68, v135
	v_readlane_b32 s63, v212, 48
	v_readlane_b32 s64, v215, 48
	v_readlane_b32 s65, v217, 48
	s_waitcnt vmcnt(15)
	v_fmac_f32_e32 v4, s63, v80
	v_fmac_f32_e32 v5, s64, v80
	v_fmac_f32_e32 v29, s65, v80
	v_readlane_b32 s66, v212, 49
	v_readlane_b32 s67, v215, 49
	v_readlane_b32 s68, v217, 49
	s_waitcnt vmcnt(14)
	v_fmac_f32_e32 v4, s66, v81
	v_fmac_f32_e32 v5, s67, v81
	v_fmac_f32_e32 v29, s68, v81
	v_readlane_b32 s63, v212, 50
	v_readlane_b32 s64, v215, 50
	v_readlane_b32 s65, v217, 50
	s_waitcnt vmcnt(13)
	v_fmac_f32_e32 v4, s63, v82
	v_fmac_f32_e32 v5, s64, v82
	v_fmac_f32_e32 v29, s65, v82
	v_readlane_b32 s66, v212, 51
	v_readlane_b32 s67, v215, 51
	v_readlane_b32 s68, v217, 51
	s_waitcnt vmcnt(12)
	v_fmac_f32_e32 v4, s66, v83
	v_fmac_f32_e32 v5, s67, v83
	v_fmac_f32_e32 v29, s68, v83
	v_readlane_b32 s63, v212, 52
	v_readlane_b32 s64, v215, 52
	v_readlane_b32 s65, v217, 52
	s_waitcnt vmcnt(11)
	v_fmac_f32_e32 v4, s63, v84
	v_fmac_f32_e32 v5, s64, v84
	v_fmac_f32_e32 v29, s65, v84
	v_readlane_b32 s66, v212, 53
	v_readlane_b32 s67, v215, 53
	v_readlane_b32 s68, v217, 53
	s_waitcnt vmcnt(10)
	v_fmac_f32_e32 v4, s66, v85
	v_fmac_f32_e32 v5, s67, v85
	v_fmac_f32_e32 v29, s68, v85
	v_readlane_b32 s63, v212, 54
	v_readlane_b32 s64, v215, 54
	v_readlane_b32 s65, v217, 54
	s_waitcnt vmcnt(9)
	v_fmac_f32_e32 v4, s63, v86
	v_fmac_f32_e32 v5, s64, v86
	v_fmac_f32_e32 v29, s65, v86
	v_readlane_b32 s66, v212, 55
	v_readlane_b32 s67, v215, 55
	v_readlane_b32 s68, v217, 55
	s_waitcnt vmcnt(8)
	v_fmac_f32_e32 v4, s66, v87
	v_fmac_f32_e32 v5, s67, v87
	v_fmac_f32_e32 v29, s68, v87
	v_readlane_b32 s63, v212, 56
	v_readlane_b32 s64, v215, 56
	v_readlane_b32 s65, v217, 56
	s_waitcnt vmcnt(7)
	v_fmac_f32_e32 v4, s63, v88
	v_fmac_f32_e32 v5, s64, v88
	v_fmac_f32_e32 v29, s65, v88
	v_readlane_b32 s66, v212, 57
	v_readlane_b32 s67, v215, 57
	v_readlane_b32 s68, v217, 57
	s_waitcnt vmcnt(6)
	v_fmac_f32_e32 v4, s66, v89
	v_fmac_f32_e32 v5, s67, v89
	v_fmac_f32_e32 v29, s68, v89
	v_readlane_b32 s63, v212, 58
	v_readlane_b32 s64, v215, 58
	v_readlane_b32 s65, v217, 58
	s_waitcnt vmcnt(5)
	v_fmac_f32_e32 v4, s63, v90
	v_fmac_f32_e32 v5, s64, v90
	v_fmac_f32_e32 v29, s65, v90
	v_readlane_b32 s66, v212, 59
	v_readlane_b32 s67, v215, 59
	v_readlane_b32 s68, v217, 59
	s_waitcnt vmcnt(4)
	v_fmac_f32_e32 v4, s66, v91
	v_fmac_f32_e32 v5, s67, v91
	v_fmac_f32_e32 v29, s68, v91
	v_readlane_b32 s63, v212, 60
	v_readlane_b32 s64, v215, 60
	v_readlane_b32 s65, v217, 60
	s_waitcnt vmcnt(3)
	v_fmac_f32_e32 v4, s63, v92
	v_fmac_f32_e32 v5, s64, v92
	v_fmac_f32_e32 v29, s65, v92
	v_readlane_b32 s66, v212, 61
	v_readlane_b32 s67, v215, 61
	v_readlane_b32 s68, v217, 61
	s_waitcnt vmcnt(2)
	v_fmac_f32_e32 v4, s66, v93
	v_fmac_f32_e32 v5, s67, v93
	v_fmac_f32_e32 v29, s68, v93
	v_readlane_b32 s63, v212, 62
	v_readlane_b32 s64, v215, 62
	v_readlane_b32 s65, v217, 62
	s_waitcnt vmcnt(1)
	v_fmac_f32_e32 v4, s63, v94
	v_fmac_f32_e32 v5, s64, v94
	v_fmac_f32_e32 v29, s65, v94
	v_readlane_b32 s66, v212, 63
	v_readlane_b32 s67, v215, 63
	v_readlane_b32 s68, v217, 63
	s_waitcnt vmcnt(0)
	v_fmac_f32_e32 v4, s66, v95
	v_fmac_f32_e32 v5, s67, v95
	v_fmac_f32_e32 v29, s68, v95
	s_mulk_i32 s24, 0x6c00
	v_add_lshl_u32 v8, v28, s24, 2
	v_lshl_add_u64 v[2:3], s[22:23], 0, v[8:9]
	v_add_co_u32_e32 v30, vcc, 0x9000, v2
	global_store_dword v8, v4, s[22:23]
	s_nop 0
	v_addc_co_u32_e32 v31, vcc, 0, v3, vcc
	v_add_co_u32_e32 v2, vcc, 0x12000, v2
	global_store_dword v[30:31], v5, off
	s_nop 0
	v_addc_co_u32_e32 v3, vcc, 0, v3, vcc
	global_store_dword v[2:3], v29, off
	s_branch .LBB0_7
